# barriers: XCD-last arriver publishes the generation word before its own acquire invalidate (on top of the single-XCD group shortcut)
# speedup vs baseline: 1.0074x; 1.0074x over previous
; __device__ __forceinline__ unsigned xb_ld(unsigned* p)              { return __hip_atomic_load(p, __ATOMIC_RELAXED, __HIP_MEMORY_SCOPE_AGENT); }
; __device__ __forceinline__ unsigned xb_add(unsigned* p, unsigned v) { return __hip_atomic_fetch_add(p, v, __ATOMIC_RELAXED, __HIP_MEMORY_SCOPE_AGENT); }
; #define XB_SPIN(cond, bar) do { unsigned _sp = 0; while (cond) { __builtin_amdgcn_s_sleep(1); \
;     if ((++_sp & 255u) == 0u) { if (xb_ld(&(bar)[XB_TMO])) break; if (_sp > XB_SPIN_CAP) { atomicAdd(&(bar)[XB_TMO], 1u); break; } } } } while (0)
; __device__ __forceinline__ void xcd_barrier(const XcdBarrier& b) {
;     ...
;             else XB_SPIN(xb_ld(&bar[XB_TOPGEN]) == tg, bar);
;             __builtin_amdgcn_fence(__ATOMIC_ACQUIRE, "agent");
;             xb_add(&bar[XB_XGEN(b.x)], 1u);
;             asm volatile("s_waitcnt vmcnt(0)" ::: "memory");
.LBB0_151:
	s_or_b64 exec, exec, s[8:9]
	s_mov_b64 s[8:9], exec
	v_mbcnt_lo_u32_b32 v0, s8, 0
	v_mbcnt_hi_u32_b32 v0, s9, v0
	v_cmp_eq_u32_e32 vcc, 0, v0
	s_waitcnt vmcnt(0)
	s_and_saveexec_b64 s[38:39], vcc
	s_cbranch_execz .LBB0_153
	s_bcnt1_i32_b64 s8, s[8:9]
	v_mov_b32_e32 v0, 0x2000
	v_mov_b32_e32 v1, s8
	global_atomic_add v0, v1, s[6:7] offset:1024
.LBB0_153:
	s_or_b64 exec, exec, s[38:39]
	buffer_inv sc1
	s_waitcnt vmcnt(0)

; __device__ __forceinline__ unsigned xb_ld(unsigned* p)              { return __hip_atomic_load(p, __ATOMIC_RELAXED, __HIP_MEMORY_SCOPE_AGENT); }
; __device__ __forceinline__ unsigned xb_add(unsigned* p, unsigned v) { return __hip_atomic_fetch_add(p, v, __ATOMIC_RELAXED, __HIP_MEMORY_SCOPE_AGENT); }
; #define XB_SPIN(cond, bar) do { unsigned _sp = 0; while (cond) { __builtin_amdgcn_s_sleep(1); \
;     if ((++_sp & 255u) == 0u) { if (xb_ld(&(bar)[XB_TMO])) break; if (_sp > XB_SPIN_CAP) { atomicAdd(&(bar)[XB_TMO], 1u); break; } } } } while (0)
; __device__ __forceinline__ void xcd_barrier(const XcdBarrier& b) {
;     ...
;             else XB_SPIN(xb_ld(&bar[XB_TOPGEN]) == tg, bar);
;             __builtin_amdgcn_fence(__ATOMIC_ACQUIRE, "agent");
;             xb_add(&bar[XB_XGEN(b.x)], 1u);
;             asm volatile("s_waitcnt vmcnt(0)" ::: "memory");
.LBB0_398:
	s_or_b64 exec, exec, s[8:9]
	s_mov_b64 s[8:9], exec
	v_mbcnt_lo_u32_b32 v0, s8, 0
	v_mbcnt_hi_u32_b32 v0, s9, v0
	v_cmp_eq_u32_e32 vcc, 0, v0
	s_waitcnt vmcnt(0)
	s_and_saveexec_b64 s[12:13], vcc
	s_cbranch_execz .LBB0_400
	s_bcnt1_i32_b64 s8, s[8:9]
	v_mov_b32_e32 v0, 0x2000
	v_mov_b32_e32 v1, s8
	global_atomic_add v0, v1, s[6:7] offset:1024
.LBB0_400:
	s_or_b64 exec, exec, s[12:13]
	buffer_inv sc1
	s_waitcnt vmcnt(0)

; __device__ __forceinline__ unsigned xb_add(unsigned* p, unsigned v) { return __hip_atomic_fetch_add(p, v, __ATOMIC_RELAXED, __HIP_MEMORY_SCOPE_AGENT); }
; __device__ __forceinline__ void xcd_barrier(const XcdBarrier& b) {
;     ...
;             xb_add(&bar[XB_XGEN(b.x)], 1u);
;             asm volatile("s_waitcnt vmcnt(0)" ::: "memory");
.Lgb_skip_0:
	v_mov_b32_e32 v0, 0x2000
	v_mov_b32_e32 v1, 1
	s_waitcnt vmcnt(0)
	global_atomic_add v0, v1, s[6:7] offset:1024
	buffer_inv sc1
	s_waitcnt vmcnt(0)

; __device__ __forceinline__ unsigned xb_ld(unsigned* p)              { return __hip_atomic_load(p, __ATOMIC_RELAXED, __HIP_MEMORY_SCOPE_AGENT); }
; __device__ __forceinline__ unsigned xb_add(unsigned* p, unsigned v) { return __hip_atomic_fetch_add(p, v, __ATOMIC_RELAXED, __HIP_MEMORY_SCOPE_AGENT); }
; #define XB_SPIN(cond, bar) do { unsigned _sp = 0; while (cond) { __builtin_amdgcn_s_sleep(1); \
;     if ((++_sp & 255u) == 0u) { if (xb_ld(&(bar)[XB_TMO])) break; if (_sp > XB_SPIN_CAP) { atomicAdd(&(bar)[XB_TMO], 1u); break; } } } } while (0)
; __device__ __forceinline__ void xcd_barrier(const XcdBarrier& b) {
;     ...
;             else XB_SPIN(xb_ld(&bar[XB_TOPGEN]) == tg, bar);
;             __builtin_amdgcn_fence(__ATOMIC_ACQUIRE, "agent");
;             xb_add(&bar[XB_XGEN(b.x)], 1u);
;             asm volatile("s_waitcnt vmcnt(0)" ::: "memory");
.LBB0_667:
	s_or_b64 exec, exec, s[12:13]
	s_mov_b64 s[12:13], exec
	v_mbcnt_lo_u32_b32 v0, s12, 0
	v_mbcnt_hi_u32_b32 v0, s13, v0
	v_cmp_eq_u32_e32 vcc, 0, v0
	s_waitcnt vmcnt(0)
	s_and_saveexec_b64 s[16:17], vcc
	s_cbranch_execz .LBB0_669
	s_bcnt1_i32_b64 s10, s[12:13]
	v_mov_b32_e32 v0, 0x2000
	v_mov_b32_e32 v1, s10
	global_atomic_add v0, v1, s[8:9] offset:1024
.LBB0_669:
	s_or_b64 exec, exec, s[16:17]
	buffer_inv sc1
	s_waitcnt vmcnt(0)

; __device__ __forceinline__ unsigned xb_add(unsigned* p, unsigned v) { return __hip_atomic_fetch_add(p, v, __ATOMIC_RELAXED, __HIP_MEMORY_SCOPE_AGENT); }
; __device__ __forceinline__ void xcd_barrier(const XcdBarrier& b) {
;     ...
;             xb_add(&bar[XB_XGEN(b.x)], 1u);
;             asm volatile("s_waitcnt vmcnt(0)" ::: "memory");
.Lgb_skip_1:
	v_mov_b32_e32 v0, 0x2000
	v_mov_b32_e32 v1, 1
	s_waitcnt vmcnt(0)
	global_atomic_add v0, v1, s[4:5] offset:1024
	buffer_inv sc1
	s_waitcnt vmcnt(0)

; __device__ __forceinline__ unsigned xb_ld(unsigned* p)              { return __hip_atomic_load(p, __ATOMIC_RELAXED, __HIP_MEMORY_SCOPE_AGENT); }
; __device__ __forceinline__ unsigned xb_add(unsigned* p, unsigned v) { return __hip_atomic_fetch_add(p, v, __ATOMIC_RELAXED, __HIP_MEMORY_SCOPE_AGENT); }
; #define XB_SPIN(cond, bar) do { unsigned _sp = 0; while (cond) { __builtin_amdgcn_s_sleep(1); \
;     if ((++_sp & 255u) == 0u) { if (xb_ld(&(bar)[XB_TMO])) break; if (_sp > XB_SPIN_CAP) { atomicAdd(&(bar)[XB_TMO], 1u); break; } } } } while (0)
; __device__ __forceinline__ void xcd_barrier(const XcdBarrier& b) {
;     ...
;             else XB_SPIN(xb_ld(&bar[XB_TOPGEN]) == tg, bar);
;             __builtin_amdgcn_fence(__ATOMIC_ACQUIRE, "agent");
;             xb_add(&bar[XB_XGEN(b.x)], 1u);
;             asm volatile("s_waitcnt vmcnt(0)" ::: "memory");
.LBB0_1209:
	s_or_b64 exec, exec, s[6:7]
	s_mov_b64 s[6:7], exec
	v_mbcnt_lo_u32_b32 v0, s6, 0
	v_mbcnt_hi_u32_b32 v0, s7, v0
	v_cmp_eq_u32_e32 vcc, 0, v0
	s_waitcnt vmcnt(0)
	s_and_saveexec_b64 s[8:9], vcc
	s_cbranch_execz .LBB0_1211
	s_bcnt1_i32_b64 s6, s[6:7]
	v_mov_b32_e32 v0, 0x2000
	v_mov_b32_e32 v1, s6
	global_atomic_add v0, v1, s[4:5] offset:1024
.LBB0_1211:
	s_or_b64 exec, exec, s[8:9]
	buffer_inv sc1
	s_waitcnt vmcnt(0)
